# v74 + static s_setprio 1 for the two sample-attention waves during the mixers' barrier-free tail (reset to 0 at the tail end)
# speedup vs baseline: 1.0040x; 1.0040x over previous
.LBB0_456:
	s_andn2_saveexec_b64 s[10:11], s[4:5]
	s_cbranch_execz .LBB0_463
	s_setprio 1
	v_lshl_add_u32 v53, s20, 1, v1
	s_movk_i32 s0, 0x200
	v_cmp_gt_i32_e32 vcc, s0, v53
	s_and_saveexec_b64 s[12:13], vcc
	s_cbranch_execz .LBB0_462
	v_and_b32_e32 v52, 63, v0
	v_lshrrev_b32_e32 v0, 6, v0
	s_waitcnt vmcnt(0)
	v_lshl_add_u32 v66, v1, 12, 16
	v_lshlrev_b32_e32 v54, 2, v52
	v_sub_u32_e32 v1, 0x80, v52
	v_or_b32_e32 v69, 64, v52
	v_readlane_b32 s36, v254, 14
	s_lshl_b32 s0, s20, 1
	v_mbcnt_hi_u32_b32 v77, -1, v185
	v_mov_b32_e32 v55, 0
	v_cvt_f32_ubyte0_e32 v68, v1
	v_sub_u32_e32 v1, 0x80, v69
	v_add_u32_e32 v71, v66, v54
	v_readlane_b32 s42, v254, 20
	v_readlane_b32 s43, v254, 21
	v_add_u16_e32 v73, s0, v0
	v_and_b32_e32 v0, 64, v77
	v_lshl_add_u32 v67, v52, 4, v66
	v_cmp_eq_u32_e64 s[4:5], 0, v52
	v_cvt_f32_ubyte0_e32 v70, v1
	s_lshl_b32 s14, s22, 1
	v_add_u32_e32 v72, 0x400, v66
	v_lshl_add_u64 v[56:57], s[42:43], 0, v[54:55]
	s_mov_b64 s[54:55], 0
	s_movk_i32 s15, 0x2000
	v_lshlrev_b32_e32 v58, 1, v54
	v_mov_b32_e32 v59, v55
	s_mov_b32 s21, 0xc2fc0000
	v_mov_b32_e32 v74, 0x42800000
	v_not_b32_e32 v75, 63
	v_mov_b32_e32 v76, 0xf149f2ca
	v_add_u32_e32 v78, 64, v0
	v_xor_b32_e32 v79, 1, v77
	v_xor_b32_e32 v80, 2, v77
	v_xor_b32_e32 v81, 4, v77
	v_xor_b32_e32 v82, 8, v77
	v_xor_b32_e32 v83, 16, v77
	v_xor_b32_e32 v84, 32, v77
	s_movk_i32 s24, 0x3000
	s_movk_i32 s25, 0x1ff
	v_add_u32_e32 v85, 16, v71
	v_add_u32_e32 v86, 32, v71
	v_add_u32_e32 v87, 48, v71
	v_readlane_b32 s37, v254, 15
	v_readlane_b32 s38, v254, 16
	v_readlane_b32 s39, v254, 17
	v_readlane_b32 s40, v254, 18
	v_readlane_b32 s41, v254, 19
	v_readlane_b32 s44, v254, 22
	v_readlane_b32 s45, v254, 23
	v_readlane_b32 s46, v254, 24
	v_readlane_b32 s47, v254, 25
	v_readlane_b32 s48, v254, 26
	v_readlane_b32 s49, v254, 27
	v_readlane_b32 s50, v254, 28
	v_readlane_b32 s51, v254, 29

.LBB0_463:
	s_or_b64 exec, exec, s[10:11]
	s_setprio 0
	s_waitcnt vmcnt(0)
	s_waitcnt lgkmcnt(0)
	s_barrier
	s_and_saveexec_b64 s[0:1], s[18:19]
	s_cbranch_execz .LBB0_515
	s_add_i32 s2, 16, 0x20040
	v_mov_b32_e32 v0, s2
	s_waitcnt vmcnt(0) expcnt(0) lgkmcnt(0)
	ds_read_b32 v2, v0
	s_add_i32 s2, 16, 0x20044
	v_mov_b32_e32 v0, s2
	ds_read_b32 v0, v0
	s_waitcnt lgkmcnt(1)
	v_cmp_ne_u32_e32 vcc, 0, v2
	s_cbranch_vccnz .LBB0_479
	v_readlane_b32 s2, v254, 9
	v_readlane_b32 s3, v254, 10
	s_load_dword s2, s[2:3], 0x14
	s_mov_b32 s21, 1
	v_mov_b32_e32 v16, 0
	s_waitcnt lgkmcnt(0)
	s_lshr_b32 s4, s2, 16
	s_and_b32 s2, s2, 0xffff
	s_cmp_lg_u32 s2, 0
	s_cselect_b64 s[2:3], -1, 0
	s_cmp_lg_u64 s[2:3], 0
	s_addc_u32 s2, s23, 0
	s_cmp_lg_u32 s4, 0
	s_mul_i32 s33, s2, s22
	s_cselect_b64 s[2:3], -1, 0
	s_cmp_lg_u64 s[2:3], 0
	v_readlane_b32 s2, v254, 8
	s_addc_u32 s2, s2, 0
	s_mul_i32 s33, s33, s2
	s_add_u32 s2, s70, 0xa0200
	s_addc_u32 s3, s71, 0
	s_add_u32 s4, s70, 0xa0400
	s_addc_u32 s5, s71, 0
	s_add_u32 s6, s70, 0xa0500
	s_addc_u32 s7, s71, 0
	s_add_u32 s8, s70, 0xa0600
	s_addc_u32 s9, s71, 0
	s_add_u32 s10, s70, 0xa0700
	s_addc_u32 s11, s71, 0
	s_add_u32 s12, s70, 0xa0800
	s_addc_u32 s13, s71, 0
	s_add_u32 s14, s70, 0xa0900
	s_addc_u32 s15, s71, 0
	s_add_u32 s16, s70, 0xa0a00
	s_addc_u32 s17, s71, 0
	s_add_u32 s24, s70, 0xa0b00
	s_addc_u32 s25, s71, 0
	s_add_u32 s26, s70, 0xa0c00
	s_addc_u32 s27, s71, 0
	s_add_u32 s28, s70, 0xa0d00
	s_addc_u32 s29, s71, 0
	s_add_u32 s30, s70, 0xa0e00
	s_addc_u32 s31, s71, 0
	s_add_u32 s34, s70, 0xa0f00
	s_addc_u32 s35, s71, 0
	s_add_u32 s52, s70, 0xa1000
	s_addc_u32 s53, s71, 0
	s_add_u32 s54, s70, 0xa1100
	s_addc_u32 s55, s71, 0
	s_add_u32 s72, s70, 0xa1200
	s_addc_u32 s73, s71, 0
	s_add_u32 s74, s70, 0xa1300
	s_addc_u32 s75, s71, 0
	s_branch .LBB0_467

.LBB0_1391:
	s_andn2_saveexec_b64 s[14:15], s[2:3]
	s_cbranch_execz .LBB0_1398
	s_setprio 1
	v_lshl_add_u32 v53, s20, 1, v1
	s_movk_i32 s0, 0x200
	v_cmp_gt_i32_e32 vcc, s0, v53
	s_and_saveexec_b64 s[16:17], vcc
	s_cbranch_execz .LBB0_1397
	v_readlane_b32 s36, v254, 14
	v_readlane_b32 s40, v254, 18
	v_readlane_b32 s41, v254, 19
	v_readlane_b32 s42, v254, 20
	v_readlane_b32 s43, v254, 21
	s_mov_b64 s[8:9], s[40:41]
	v_and_b32_e32 v52, 63, v0
	s_add_u32 s30, s8, 0x1000000
	s_addc_u32 s31, s9, 0
	v_lshrrev_b32_e32 v0, 6, v0
	v_lshl_add_u32 v66, v1, 12, 16
	v_lshlrev_b32_e32 v54, 2, v52
	v_sub_u32_e32 v1, 0x80, v52
	v_or_b32_e32 v69, 64, v52
	s_lshl_b32 s0, s20, 1
	v_mbcnt_hi_u32_b32 v77, -1, v185
	s_mov_b64 s[10:11], s[42:43]
	v_mov_b32_e32 v55, 0
	v_cvt_f32_ubyte0_e32 v68, v1
	v_sub_u32_e32 v1, 0x80, v69
	v_add_u32_e32 v71, v66, v54
	v_add_u16_e32 v73, s0, v0
	v_and_b32_e32 v0, 64, v77
	v_lshl_add_u32 v67, v52, 4, v66
	v_cmp_eq_u32_e64 s[2:3], 0, v52
	v_cvt_f32_ubyte0_e32 v70, v1
	s_lshl_b32 s8, s22, 1
	v_add_u32_e32 v72, 0x400, v66
	v_lshl_add_u64 v[56:57], s[10:11], 0, v[54:55]
	s_mov_b64 s[34:35], 0
	v_lshlrev_b32_e32 v58, 1, v54
	v_mov_b32_e32 v59, v55
	s_mov_b32 s9, 0xc2fc0000
	v_mov_b32_e32 v74, 0x42800000
	v_not_b32_e32 v75, 63
	v_mov_b32_e32 v76, 0xf149f2ca
	v_add_u32_e32 v78, 64, v0
	v_xor_b32_e32 v79, 1, v77
	v_xor_b32_e32 v80, 2, v77
	v_xor_b32_e32 v81, 4, v77
	v_xor_b32_e32 v82, 8, v77
	v_xor_b32_e32 v83, 16, v77
	v_xor_b32_e32 v84, 32, v77
	s_movk_i32 s21, 0x1ff
	v_add_u32_e32 v85, 16, v71
	v_add_u32_e32 v86, 32, v71
	v_add_u32_e32 v87, 48, v71
	v_readlane_b32 s37, v254, 15
	v_readlane_b32 s38, v254, 16
	v_readlane_b32 s39, v254, 17
	v_readlane_b32 s44, v254, 22
	v_readlane_b32 s45, v254, 23
	v_readlane_b32 s46, v254, 24
	v_readlane_b32 s47, v254, 25
	v_readlane_b32 s48, v254, 26
	v_readlane_b32 s49, v254, 27
	v_readlane_b32 s50, v254, 28
	v_readlane_b32 s51, v254, 29

.LBB0_1398:
	s_or_b64 exec, exec, s[14:15]
	s_setprio 0
	s_waitcnt vmcnt(0)
	s_waitcnt lgkmcnt(0)
	s_barrier
	s_and_saveexec_b64 s[0:1], s[18:19]
	s_cbranch_execz .LBB0_1450
	s_add_i32 s2, 16, 0x20040
	v_mov_b32_e32 v0, s2
	s_waitcnt vmcnt(0) expcnt(0) lgkmcnt(0)
	ds_read_b32 v2, v0
	s_add_i32 s2, 16, 0x20044
	v_mov_b32_e32 v0, s2
	ds_read_b32 v0, v0
	s_waitcnt lgkmcnt(1)
	v_cmp_ne_u32_e32 vcc, 0, v2
	s_cbranch_vccnz .LBB0_1414
	v_readlane_b32 s2, v254, 9
	v_readlane_b32 s3, v254, 10
	s_load_dword s2, s[2:3], 0x14
	s_mov_b32 s21, 1
	v_mov_b32_e32 v16, 0
	s_waitcnt lgkmcnt(0)
	s_lshr_b32 s4, s2, 16
	s_and_b32 s2, s2, 0xffff
	s_cmp_lg_u32 s2, 0
	s_cselect_b64 s[2:3], -1, 0
	s_cmp_lg_u64 s[2:3], 0
	s_addc_u32 s2, s23, 0
	s_cmp_lg_u32 s4, 0
	s_mul_i32 s24, s2, s22
	s_cselect_b64 s[2:3], -1, 0
	s_cmp_lg_u64 s[2:3], 0
	v_readlane_b32 s2, v254, 8
	s_addc_u32 s2, s2, 0
	s_mul_i32 s24, s24, s2
	s_add_u32 s2, s70, 0xa0200
	s_addc_u32 s3, s71, 0
	s_add_u32 s4, s70, 0xa0400
	s_addc_u32 s5, s71, 0
	s_add_u32 s6, s70, 0xa0500
	s_addc_u32 s7, s71, 0
	s_add_u32 s8, s70, 0xa0600
	s_addc_u32 s9, s71, 0
	s_add_u32 s10, s70, 0xa0700
	s_addc_u32 s11, s71, 0
	s_add_u32 s12, s70, 0xa0800
	s_addc_u32 s13, s71, 0
	s_add_u32 s14, s70, 0xa0900
	s_addc_u32 s15, s71, 0
	s_add_u32 s16, s70, 0xa0a00
	s_addc_u32 s17, s71, 0
	s_add_u32 s26, s70, 0xa0b00
	s_addc_u32 s27, s71, 0
	s_add_u32 s28, s70, 0xa0c00
	s_addc_u32 s29, s71, 0
	s_add_u32 s30, s70, 0xa0d00
	s_addc_u32 s31, s71, 0
	s_add_u32 s34, s70, 0xa0e00
	s_addc_u32 s35, s71, 0
	s_add_u32 s36, s70, 0xa0f00
	s_addc_u32 s37, s71, 0
	s_add_u32 s38, s70, 0xa1000
	s_addc_u32 s39, s71, 0
	s_add_u32 s40, s70, 0xa1100
	s_addc_u32 s41, s71, 0
	s_add_u32 s42, s70, 0xa1200
	s_addc_u32 s43, s71, 0
	s_add_u32 s44, s70, 0xa1300
	s_addc_u32 s45, s71, 0
	s_branch .LBB0_1402
